# P2 item order rebalanced: 6 of 8 XCD slots run retention first (S5-first group was the later finisher by ~10us per layer)
# baseline (speedup 1.0000x reference)
; __device__ __forceinline__ void p2_ret(const Frame& F, ArgsP a, int layer) {
;     ...
;     const bf16_t* qg = (const bf16_t*)(F.ws + WS_Q); const bf16_t* kg = (const bf16_t*)(F.ws + WS_K); const bf16_t* vtg = (const bf16_t*)(F.ws + WS_VT);
;     const bf16_t* grg = (const bf16_t*)(F.ws + WS_GR); bf16_t* ycat = (bf16_t*)(F.ws + WS_YCAT);
;     const __amdgpu_buffer_rsrc_t RK = __builtin_amdgcn_make_buffer_rsrc((void*)kg, (short)0, 0x7ffffff0, 0x00020000), RV = __builtin_amdgcn_make_buffer_rsrc((void*)vtg, (short)0, 0x7ffffff0, 0x00020000);
;     ...
;     const int cvw = F.vcu * 8 + w, cvs = F.G * 8, CV_HALF_ITEMS = (layer + 1 < DEPTH) ? CV_HALF_L0 : CV_HALF_L1; int cvhi = cvw, cvtile = F.vcu & 1;
; __global__ void __launch_bounds__(512, 2) mk_fwd(Args args) {
;     ...
;         else { const int l = (ph - 1) >> 2, s = (ph - 1) & 3;
;             if (s == 0) p1_inproj(F, l);
;             else if (s == 1) { int sw = F.bid & 1; asm volatile("" : "+s"(sw));
; #pragma unroll 1
;                 for (int it = 0; it < 2; ++it) { if ((it ^ sw) == 0) p2_ssm(F, ap, l); else p2_ret(F, ap, l); } }
.LBB0_346:
	s_and_b64 vcc, exec, s[2:3]
	s_cbranch_vccz .LBB0_515
	s_and_b32 s2, s65, 5
	s_cmp_eq_u32 s2, 0
	s_cselect_b32 s3, 1, 0
	s_and_b32 s2, s65, 1
	s_or_b32 s2, s2, s3
	s_mov_b32 s42, s86
	v_writelane_b32 v255, s2, 37
	s_mov_b32 s43, s87
	v_readlane_b32 s4, v255, 24
	v_readlane_b32 s5, v255, 25
	s_add_u32 s2, s4, 0x29000000
	s_addc_u32 s3, s5, 0
	v_writelane_b32 v255, s2, 30
	s_add_u32 s40, s4, 0x2b000000
	s_mov_b64 s[6:7], -1
	v_writelane_b32 v255, s3, 31
	s_addc_u32 s2, s5, 0
	s_add_u32 s44, s4, 0x2d000000
	s_addc_u32 s3, s5, 0
	s_and_b32 s41, s2, 0xffff
	s_lshl_b32 s2, s93, 3
	s_and_b32 s45, s3, 0xffff
	s_add_i32 s2, s2, s91
	v_writelane_b32 v255, s2, 38
	s_cmp_lt_i32 s48, 1
	s_mov_b32 s2, 0x8800
	s_mov_b32 s3, s93
	s_cselect_b32 s93, s2, 0x2800
	s_cmpk_lt_i32 s3, 0x100
	s_cselect_b64 s[2:3], -1, 0
	v_writelane_b32 v255, s2, 39
	s_add_i32 s54, s48, 1
	s_nop 0
	v_writelane_b32 v255, s3, 40
	s_add_u32 s2, s4, s18
	s_addc_u32 s3, s5, 0
	s_add_u32 s2, s2, 0x2f000000
	v_writelane_b32 v255, s2, 32
	s_addc_u32 s2, s3, 0
	s_add_u32 s9, s4, 0xd000000
	s_addc_u32 s58, s5, 0
	s_add_u32 s59, s4, 0x1000000
	s_addc_u32 s53, s5, 0
	s_add_u32 s8, s4, 0xe000000
	v_writelane_b32 v255, s2, 34
	s_addc_u32 s94, s5, 0
	s_lshl_b32 s2, s48, 7
	s_ashr_i32 s49, s48, 31
	v_writelane_b32 v255, s2, 41
	s_lshl_b64 s[2:3], s[48:49], 13
	v_writelane_b32 v255, s2, 42
	s_nop 1
	v_writelane_b32 v255, s3, 43
	s_add_u32 s2, s4, 0x24000000
	v_writelane_b32 v255, s2, 44
	s_addc_u32 s2, s5, 0
	v_writelane_b32 v255, s2, 45
	s_add_u32 s2, s4, 0x15000000
	v_writelane_b32 v255, s2, 46
	s_addc_u32 s2, s5, 0
	v_writelane_b32 v255, s2, 47
	s_add_u32 s2, s4, 0x17000000
	s_addc_u32 s3, s5, 0
	v_writelane_b32 v255, s2, 48
	s_nop 1
	v_writelane_b32 v255, s3, 49
	s_add_u32 s2, s4, 0x12000000
	v_writelane_b32 v255, s2, 50
	s_addc_u32 s2, s5, 0
	v_writelane_b32 v255, s2, 51
	s_add_u32 s2, s4, 0x31000000
	s_addc_u32 s3, s5, 0
	v_writelane_b32 v255, s2, 52
	s_add_u32 s60, s4, 0x1c000000
	s_addc_u32 s61, s5, 0
	v_writelane_b32 v255, s3, 53
	s_ashr_i32 s55, s54, 31
	s_mov_b32 s2, 0
	s_branch .LBB0_349
